# memory attention: LDS operand reads of the QK^T and PV MFMA sections pipelined through a 3-deep register ring
# baseline (speedup 1.0000x reference)
.LBB0_191:
	v_mov_b32_e32 v79, v46
	v_cndmask_b32_e64 v46, 0, 1, s[0:1]
	v_cmp_ne_u32_e32 vcc, 1, v46
	v_lshl_or_b32 v46, s6, 7, v72
	v_mad_u32_u24 v78, v46, s73, v73
	ds_read_b128 v[102:105], v78
	ds_read_b128 v[106:109], v78 offset:64
	ds_read_b128 v[110:113], v78 offset:128
	ds_read_b128 v[114:117], v78 offset:192
	ds_read_b128 v[118:121], v78 offset:4352
	ds_read_b128 v[122:125], v78 offset:4416
	ds_read_b128 v[126:129], v78 offset:4480
	ds_read_b128 v[130:133], v78 offset:4544
	ds_read_b128 v[134:137], v78 offset:8704
	ds_read_b128 v[138:141], v78 offset:8768
	ds_read_b128 v[142:145], v78 offset:8832
	ds_read_b128 v[146:149], v78 offset:8896
	s_and_b64 vcc, exec, vcc
	s_waitcnt vmcnt(0)
	s_waitcnt lgkmcnt(8)
	v_mfma_f32_16x16x32_bf16 v[46:49], v[102:105], v[6:9], 0
	v_mfma_f32_16x16x32_bf16 v[46:49], v[106:109], v[10:13], v[46:49]
	v_mfma_f32_16x16x32_bf16 v[46:49], v[110:113], v[14:17], v[46:49]
	v_mfma_f32_16x16x32_bf16 v[46:49], v[114:117], v[18:21], v[46:49]
	ds_read_b128 v[102:105], v78 offset:13056
	ds_read_b128 v[106:109], v78 offset:13120
	ds_read_b128 v[110:113], v78 offset:13184
	ds_read_b128 v[114:117], v78 offset:13248
	s_waitcnt lgkmcnt(8)
	v_mfma_f32_16x16x32_bf16 v[50:53], v[118:121], v[6:9], 0
	v_mfma_f32_16x16x32_bf16 v[50:53], v[122:125], v[10:13], v[50:53]
	v_mfma_f32_16x16x32_bf16 v[50:53], v[126:129], v[14:17], v[50:53]
	v_mfma_f32_16x16x32_bf16 v[50:53], v[130:133], v[18:21], v[50:53]
	ds_read_b128 v[118:121], v78 offset:17408
	ds_read_b128 v[122:125], v78 offset:17472
	ds_read_b128 v[126:129], v78 offset:17536
	ds_read_b128 v[130:133], v78 offset:17600
	s_waitcnt lgkmcnt(8)
	v_mfma_f32_16x16x32_bf16 v[58:61], v[134:137], v[6:9], 0
	v_mfma_f32_16x16x32_bf16 v[58:61], v[138:141], v[10:13], v[58:61]
	v_mfma_f32_16x16x32_bf16 v[58:61], v[142:145], v[14:17], v[58:61]
	v_mfma_f32_16x16x32_bf16 v[58:61], v[146:149], v[18:21], v[58:61]
	ds_read_b128 v[134:137], v78 offset:21760
	ds_read_b128 v[138:141], v78 offset:21824
	ds_read_b128 v[142:145], v78 offset:21888
	ds_read_b128 v[146:149], v78 offset:21952
	s_waitcnt lgkmcnt(8)
	v_mfma_f32_16x16x32_bf16 v[80:83], v[102:105], v[6:9], 0
	v_mfma_f32_16x16x32_bf16 v[80:83], v[106:109], v[10:13], v[80:83]
	v_mfma_f32_16x16x32_bf16 v[80:83], v[110:113], v[14:17], v[80:83]
	v_mfma_f32_16x16x32_bf16 v[80:83], v[114:117], v[18:21], v[80:83]
	ds_read_b128 v[102:105], v78 offset:26112
	ds_read_b128 v[106:109], v78 offset:26176
	ds_read_b128 v[110:113], v78 offset:26240
	ds_read_b128 v[114:117], v78 offset:26304
	s_waitcnt lgkmcnt(8)
	v_mfma_f32_16x16x32_bf16 v[84:87], v[118:121], v[6:9], 0
	v_mfma_f32_16x16x32_bf16 v[84:87], v[122:125], v[10:13], v[84:87]
	v_mfma_f32_16x16x32_bf16 v[84:87], v[126:129], v[14:17], v[84:87]
	v_mfma_f32_16x16x32_bf16 v[84:87], v[130:133], v[18:21], v[84:87]
	ds_read_b128 v[118:121], v78 offset:30464
	ds_read_b128 v[122:125], v78 offset:30528
	ds_read_b128 v[126:129], v78 offset:30592
	ds_read_b128 v[130:133], v78 offset:30656
	s_waitcnt lgkmcnt(8)
	v_mfma_f32_16x16x32_bf16 v[88:91], v[134:137], v[6:9], 0
	v_mfma_f32_16x16x32_bf16 v[88:91], v[138:141], v[10:13], v[88:91]
	v_mfma_f32_16x16x32_bf16 v[88:91], v[142:145], v[14:17], v[88:91]
	v_mfma_f32_16x16x32_bf16 v[88:91], v[146:149], v[18:21], v[88:91]
	s_waitcnt lgkmcnt(4)
	v_mfma_f32_16x16x32_bf16 v[92:95], v[102:105], v[6:9], 0
	v_mfma_f32_16x16x32_bf16 v[92:95], v[106:109], v[10:13], v[92:95]
	v_mfma_f32_16x16x32_bf16 v[92:95], v[110:113], v[14:17], v[92:95]
	v_mfma_f32_16x16x32_bf16 v[92:95], v[114:117], v[18:21], v[92:95]
	s_waitcnt lgkmcnt(0)
	v_mfma_f32_16x16x32_bf16 v[96:99], v[118:121], v[6:9], 0
	v_mfma_f32_16x16x32_bf16 v[96:99], v[122:125], v[10:13], v[96:99]
	v_mfma_f32_16x16x32_bf16 v[96:99], v[126:129], v[14:17], v[96:99]
	v_mfma_f32_16x16x32_bf16 v[96:99], v[130:133], v[18:21], v[96:99]
	v_lshl_add_u32 v150, s6, 8, v76
	ds_read_b128 v[102:105], v150
	ds_read_b128 v[106:109], v150 offset:64
	ds_read_b128 v[110:113], v150 offset:128
	ds_read_b128 v[114:117], v150 offset:192
	ds_read_b128 v[118:121], v150 offset:8448
	ds_read_b128 v[122:125], v150 offset:8512
	ds_read_b128 v[126:129], v150 offset:8576
	ds_read_b128 v[130:133], v150 offset:8640
	ds_read_b128 v[134:137], v150 offset:16896
	ds_read_b128 v[138:141], v150 offset:16960
	ds_read_b128 v[142:145], v150 offset:17024
	ds_read_b128 v[146:149], v150 offset:17088
	s_nop 4
	v_max3_f32 v62, v0, v46, v47
	v_max3_f32 v62, v62, v48, v49
	v_max3_f32 v62, v62, v50, v51
	v_max3_f32 v62, v62, v52, v53
	v_max3_f32 v62, v62, v58, v59
	v_max3_f32 v62, v62, v60, v61
	v_max3_f32 v62, v62, v80, v81
	v_max3_f32 v62, v62, v82, v83
	v_max3_f32 v62, v62, v84, v85
	v_max3_f32 v62, v62, v86, v87
	v_max3_f32 v62, v62, v88, v89
	v_max3_f32 v62, v62, v90, v91
	v_max3_f32 v62, v62, v92, v93
	v_max3_f32 v62, v62, v94, v95
	v_max3_f32 v62, v62, v96, v97
	v_max3_f32 v62, v62, v98, v99
	ds_bpermute_b32 v63, v74, v62
	s_waitcnt lgkmcnt(0)
	v_max_f32_e32 v63, v63, v63
	v_max_f32_e32 v62, v62, v63
	ds_bpermute_b32 v63, v75, v62
	s_waitcnt lgkmcnt(0)
	v_max_f32_e32 v63, v63, v63
	v_max_f32_e32 v78, v62, v63
	v_sub_f32_e32 v46, v46, v78
	v_exp_f32_e32 v46, v46
	v_sub_f32_e32 v47, v47, v78
	v_exp_f32_e32 v47, v47
	v_sub_f32_e32 v48, v48, v78
	v_exp_f32_e32 v48, v48
	v_sub_f32_e32 v49, v49, v78
	v_exp_f32_e32 v49, v49
	v_sub_f32_e32 v50, v50, v78
	v_add_f32_e32 v62, 0, v46
	v_exp_f32_e32 v50, v50
	v_sub_f32_e32 v51, v51, v78
	v_add_f32_e32 v62, v47, v62
	v_exp_f32_e32 v51, v51
	v_sub_f32_e32 v52, v52, v78
	v_add_f32_e32 v62, v48, v62
	v_exp_f32_e32 v52, v52
	v_sub_f32_e32 v53, v53, v78
	v_add_f32_e32 v62, v49, v62
	v_exp_f32_e32 v53, v53
	v_add_f32_e32 v62, v50, v62
	v_add_f32_e32 v62, v51, v62
	v_add_f32_e32 v62, v52, v62
	v_add_f32_e32 v100, v53, v62
	v_cvt_pk_bf16_f32 v62, v46, v47
	v_sub_f32_e32 v46, v58, v78
	v_cvt_pk_bf16_f32 v63, v48, v49
	v_exp_f32_e32 v46, v46
	v_sub_f32_e32 v48, v59, v78
	v_exp_f32_e32 v48, v48
	v_sub_f32_e32 v49, v60, v78
	v_cvt_pk_bf16_f32 v64, v50, v51
	v_exp_f32_e32 v49, v49
	v_sub_f32_e32 v50, v61, v78
	v_exp_f32_e32 v50, v50
	v_sub_f32_e32 v51, v80, v78
	v_cvt_pk_bf16_f32 v65, v52, v53
	v_add_f32_e32 v47, v46, v100
	v_exp_f32_e32 v51, v51
	v_sub_f32_e32 v52, v81, v78
	v_add_f32_e32 v47, v48, v47
	v_exp_f32_e32 v52, v52
	v_sub_f32_e32 v53, v82, v78
	v_add_f32_e32 v47, v49, v47
	v_exp_f32_e32 v53, v53
	v_sub_f32_e32 v58, v83, v78
	v_add_f32_e32 v47, v50, v47
	v_exp_f32_e32 v61, v58
	v_cvt_pk_bf16_f32 v58, v46, v48
	v_sub_f32_e32 v46, v84, v78
	v_add_f32_e32 v47, v51, v47
	v_exp_f32_e32 v46, v46
	v_sub_f32_e32 v48, v85, v78
	v_add_f32_e32 v47, v52, v47
	v_cvt_pk_bf16_f32 v59, v49, v50
	v_exp_f32_e32 v48, v48
	v_sub_f32_e32 v49, v86, v78
	v_add_f32_e32 v47, v53, v47
	v_exp_f32_e32 v49, v49
	v_sub_f32_e32 v50, v87, v78
	v_add_f32_e32 v47, v61, v47
	v_cvt_pk_bf16_f32 v60, v51, v52
	v_exp_f32_e32 v51, v50
	v_sub_f32_e32 v50, v88, v78
	v_add_f32_e32 v47, v46, v47
	v_exp_f32_e32 v52, v50
	v_sub_f32_e32 v50, v89, v78
	v_cvt_pk_bf16_f32 v61, v53, v61
	v_add_f32_e32 v47, v48, v47
	v_exp_f32_e32 v53, v50
	v_sub_f32_e32 v50, v90, v78
	v_add_f32_e32 v47, v49, v47
	v_exp_f32_e32 v80, v50
	v_sub_f32_e32 v50, v91, v78
	v_add_f32_e32 v47, v51, v47
	v_exp_f32_e32 v81, v50
	v_cvt_pk_bf16_f32 v50, v46, v48
	v_sub_f32_e32 v46, v92, v78
	v_add_f32_e32 v47, v52, v47
	v_exp_f32_e32 v46, v46
	v_sub_f32_e32 v48, v93, v78
	v_add_f32_e32 v47, v53, v47
	v_cvt_pk_bf16_f32 v51, v49, v51
	v_exp_f32_e32 v48, v48
	v_sub_f32_e32 v49, v94, v78
	v_add_f32_e32 v47, v80, v47
	v_cvt_pk_bf16_f32 v52, v52, v53
	v_cvt_pk_bf16_f32 v53, v80, v81
	v_exp_f32_e32 v49, v49
	v_sub_f32_e32 v80, v95, v78
	v_add_f32_e32 v47, v81, v47
	v_exp_f32_e32 v80, v80
	v_sub_f32_e32 v81, v96, v78
	v_add_f32_e32 v47, v46, v47
	v_exp_f32_e32 v81, v81
	v_sub_f32_e32 v82, v97, v78
	v_add_f32_e32 v47, v48, v47
	v_exp_f32_e32 v82, v82
	v_sub_f32_e32 v83, v98, v78
	v_add_f32_e32 v47, v49, v47
	v_exp_f32_e32 v83, v83
	v_sub_f32_e32 v84, v99, v78
	v_add_f32_e32 v47, v80, v47
	v_exp_f32_e32 v84, v84
	v_add_f32_e32 v47, v81, v47
	v_sub_f32_e32 v0, v0, v78
	v_add_f32_e32 v47, v82, v47
	v_add_f32_e32 v47, v83, v47
	v_cmp_gt_f32_e64 s[0:1], s9, v0
	v_add_f32_e32 v85, v84, v47
	v_cvt_pk_bf16_f32 v47, v49, v80
	v_cvt_pk_bf16_f32 v46, v46, v48
	v_cvt_pk_bf16_f32 v48, v81, v82
	v_lshl_add_u32 v82, s6, 8, v76
	v_cndmask_b32_e64 v80, 0, v225, s[0:1]
	v_add_f32_e32 v0, v0, v80
	v_exp_f32_e32 v0, v0
	v_cndmask_b32_e64 v80, 0, v226, s[0:1]
	v_cvt_pk_bf16_f32 v49, v83, v84
	s_mov_b64 s[0:1], 0
	v_ldexp_f32 v0, v0, v80
	ds_bpermute_b32 v80, v74, v85
	v_pk_mul_f32 v[56:57], v[56:57], v[0:1] op_sel_hi:[1,0]
	v_pk_mul_f32 v[54:55], v[54:55], v[0:1] op_sel_hi:[1,0]
	v_pk_mul_f32 v[40:41], v[40:41], v[0:1] op_sel_hi:[1,0]
	v_pk_mul_f32 v[38:39], v[38:39], v[0:1] op_sel_hi:[1,0]
	v_pk_mul_f32 v[36:37], v[36:37], v[0:1] op_sel_hi:[1,0]
	v_pk_mul_f32 v[34:35], v[34:35], v[0:1] op_sel_hi:[1,0]
	v_pk_mul_f32 v[32:33], v[32:33], v[0:1] op_sel_hi:[1,0]
	v_pk_mul_f32 v[30:31], v[30:31], v[0:1] op_sel_hi:[1,0]
	v_pk_mul_f32 v[28:29], v[28:29], v[0:1] op_sel_hi:[1,0]
	v_pk_mul_f32 v[26:27], v[26:27], v[0:1] op_sel_hi:[1,0]
	v_pk_mul_f32 v[4:5], v[4:5], v[0:1] op_sel_hi:[1,0]
	v_pk_mul_f32 v[2:3], v[2:3], v[0:1] op_sel_hi:[1,0]
	v_pk_mul_f32 v[24:25], v[24:25], v[0:1] op_sel_hi:[1,0]
	v_pk_mul_f32 v[22:23], v[22:23], v[0:1] op_sel_hi:[1,0]
	v_pk_mul_f32 v[44:45], v[44:45], v[0:1] op_sel_hi:[1,0]
	v_pk_mul_f32 v[42:43], v[42:43], v[0:1] op_sel_hi:[1,0]
	s_waitcnt lgkmcnt(0)
	v_add_f32_e32 v80, v85, v80
	ds_bpermute_b32 v81, v75, v80
	s_mov_b32 s6, 1
	v_mfma_f32_16x16x32_bf16 v[54:57], v[102:105], v[62:65], v[54:57]
	v_mfma_f32_16x16x32_bf16 v[54:57], v[106:109], v[58:61], v[54:57]
	v_mfma_f32_16x16x32_bf16 v[54:57], v[110:113], v[50:53], v[54:57]
	v_mfma_f32_16x16x32_bf16 v[54:57], v[114:117], v[46:49], v[54:57]
	ds_read_b128 v[102:105], v150 offset:25344
	ds_read_b128 v[106:109], v150 offset:25408
	ds_read_b128 v[110:113], v150 offset:25472
	ds_read_b128 v[114:117], v150 offset:25536
	v_mfma_f32_16x16x32_bf16 v[38:41], v[118:121], v[62:65], v[38:41]
	v_mfma_f32_16x16x32_bf16 v[38:41], v[122:125], v[58:61], v[38:41]
	v_mfma_f32_16x16x32_bf16 v[38:41], v[126:129], v[50:53], v[38:41]
	v_mfma_f32_16x16x32_bf16 v[38:41], v[130:133], v[46:49], v[38:41]
	ds_read_b128 v[118:121], v150 offset:33792
	ds_read_b128 v[122:125], v150 offset:33856
	ds_read_b128 v[126:129], v150 offset:33920
	ds_read_b128 v[130:133], v150 offset:33984
	v_mfma_f32_16x16x32_bf16 v[34:37], v[134:137], v[62:65], v[34:37]
	v_mfma_f32_16x16x32_bf16 v[34:37], v[138:141], v[58:61], v[34:37]
	v_mfma_f32_16x16x32_bf16 v[34:37], v[142:145], v[50:53], v[34:37]
	v_mfma_f32_16x16x32_bf16 v[34:37], v[146:149], v[46:49], v[34:37]
	ds_read_b128 v[134:137], v150 offset:42240
	ds_read_b128 v[138:141], v150 offset:42304
	ds_read_b128 v[142:145], v150 offset:42368
	ds_read_b128 v[146:149], v150 offset:42432
	s_waitcnt lgkmcnt(8)
	v_mfma_f32_16x16x32_bf16 v[30:33], v[102:105], v[62:65], v[30:33]
	v_mfma_f32_16x16x32_bf16 v[30:33], v[106:109], v[58:61], v[30:33]
	v_mfma_f32_16x16x32_bf16 v[30:33], v[110:113], v[50:53], v[30:33]
	v_mfma_f32_16x16x32_bf16 v[30:33], v[114:117], v[46:49], v[30:33]
	ds_read_b128 v[102:105], v150 offset:50688
	ds_read_b128 v[106:109], v150 offset:50752
	ds_read_b128 v[110:113], v150 offset:50816
	ds_read_b128 v[114:117], v150 offset:50880
	s_waitcnt lgkmcnt(8)
	v_mfma_f32_16x16x32_bf16 v[26:29], v[118:121], v[62:65], v[26:29]
	v_mfma_f32_16x16x32_bf16 v[26:29], v[122:125], v[58:61], v[26:29]
	v_mfma_f32_16x16x32_bf16 v[26:29], v[126:129], v[50:53], v[26:29]
	v_mfma_f32_16x16x32_bf16 v[26:29], v[130:133], v[46:49], v[26:29]
	ds_read_b128 v[118:121], v150 offset:59136
	ds_read_b128 v[122:125], v150 offset:59200
	ds_read_b128 v[126:129], v150 offset:59264
	ds_read_b128 v[130:133], v150 offset:59328
	s_waitcnt lgkmcnt(8)
	v_mfma_f32_16x16x32_bf16 v[2:5], v[134:137], v[62:65], v[2:5]
	v_mfma_f32_16x16x32_bf16 v[2:5], v[138:141], v[58:61], v[2:5]
	v_mfma_f32_16x16x32_bf16 v[2:5], v[142:145], v[50:53], v[2:5]
	v_mfma_f32_16x16x32_bf16 v[2:5], v[146:149], v[46:49], v[2:5]
	s_waitcnt lgkmcnt(4)
	v_mfma_f32_16x16x32_bf16 v[22:25], v[102:105], v[62:65], v[22:25]
	v_mfma_f32_16x16x32_bf16 v[22:25], v[106:109], v[58:61], v[22:25]
	v_mfma_f32_16x16x32_bf16 v[22:25], v[110:113], v[50:53], v[22:25]
	v_mfma_f32_16x16x32_bf16 v[22:25], v[114:117], v[46:49], v[22:25]
	s_waitcnt lgkmcnt(0)
	v_mfma_f32_16x16x32_bf16 v[42:45], v[118:121], v[62:65], v[42:45]
	v_mfma_f32_16x16x32_bf16 v[42:45], v[122:125], v[58:61], v[42:45]
	v_mfma_f32_16x16x32_bf16 v[42:45], v[126:129], v[50:53], v[42:45]
	v_mfma_f32_16x16x32_bf16 v[42:45], v[130:133], v[46:49], v[42:45]
	v_add_f32_e32 v46, v80, v81
	v_fmac_f32_e32 v46, v79, v0
	v_mov_b32_e32 v0, v78
	s_cbranch_vccz .LBB0_191
	v_div_scale_f32 v0, s[0:1], v46, v46, 1.0
	v_rcp_f32_e32 v6, v0
	v_div_scale_f32 v7, vcc, 1.0, v46, 1.0
	s_mov_b32 s8, 16
	v_fma_f32 v8, -v0, v6, 1.0
	v_fmac_f32_e32 v6, v8, v6
	v_mul_f32_e32 v8, v7, v6
	v_fma_f32 v9, -v0, v8, v7
	v_fmac_f32_e32 v8, v9, v6
	v_fma_f32 v0, -v0, v8, v7
	v_div_fmas_f32 v0, v0, v6, v8
	v_div_fixup_f32 v0, v0, v46, 1.0
	v_mul_f32_e32 v8, v54, v0
	v_mul_f32_e32 v9, v55, v0
	v_cvt_pk_bf16_f32 v8, v8, v9
	v_mul_f32_e32 v9, v56, v0
	v_lshl_add_u64 v[6:7], v[68:69], 0, v[70:71]
	v_mul_f32_e32 v10, v57, v0
	v_cvt_pk_bf16_f32 v9, v9, v10
	flat_store_dwordx2 v[6:7], v[8:9]
	v_mul_f32_e32 v8, v38, v0
	v_mul_f32_e32 v9, v39, v0
	v_cvt_pk_bf16_f32 v8, v8, v9
	v_mul_f32_e32 v9, v40, v0
	v_mul_f32_e32 v10, v41, v0
	v_cvt_pk_bf16_f32 v9, v9, v10
	flat_store_dwordx2 v[6:7], v[8:9] offset:32
	v_mul_f32_e32 v8, v34, v0
	v_mul_f32_e32 v9, v35, v0
	v_mul_f32_e32 v2, v0, v2
	v_mul_f32_e32 v3, v0, v3
	v_cvt_pk_bf16_f32 v8, v8, v9
	v_mul_f32_e32 v9, v36, v0
	v_cvt_pk_bf16_f32 v2, v2, v3
	v_mul_f32_e32 v3, v0, v4
	v_mul_f32_e32 v10, v37, v0
	v_cvt_pk_bf16_f32 v9, v9, v10
	v_mul_f32_e32 v4, v0, v5
	v_cvt_pk_bf16_f32 v3, v3, v4
	flat_store_dwordx2 v[6:7], v[8:9] offset:64
	v_mul_f32_e32 v8, v0, v30
	v_mul_f32_e32 v9, v0, v31
	flat_store_dwordx2 v[6:7], v[2:3] offset:160
	v_mul_f32_e32 v2, v0, v22
	v_mul_f32_e32 v3, v0, v23
	v_cvt_pk_bf16_f32 v8, v8, v9
	v_mul_f32_e32 v9, v0, v32
	v_cvt_pk_bf16_f32 v2, v2, v3
	v_mul_f32_e32 v3, v0, v24
	v_mul_f32_e32 v10, v0, v33
	v_cvt_pk_bf16_f32 v9, v9, v10
	v_mul_f32_e32 v4, v0, v25
	v_cvt_pk_bf16_f32 v3, v3, v4
	flat_store_dwordx2 v[6:7], v[8:9] offset:96
	v_mul_f32_e32 v8, v0, v26
	v_mul_f32_e32 v9, v0, v27
	flat_store_dwordx2 v[6:7], v[2:3] offset:192
	v_mul_f32_e32 v2, v0, v42
	v_mul_f32_e32 v3, v0, v43
	v_cvt_pk_bf16_f32 v8, v8, v9
	v_mul_f32_e32 v9, v0, v28
	v_cvt_pk_bf16_f32 v2, v2, v3
	v_mul_f32_e32 v3, v0, v44
	s_mov_b64 s[0:1], 0
	s_and_b64 vcc, exec, s[2:3]
	v_mul_f32_e32 v10, v0, v29
	v_cvt_pk_bf16_f32 v9, v9, v10
	flat_store_dwordx2 v[6:7], v[8:9] offset:128
	v_mul_f32_e32 v0, v0, v45
	v_cvt_pk_bf16_f32 v3, v3, v0
	flat_store_dwordx2 v[6:7], v[2:3] offset:224
	s_cbranch_vccz .LBB0_190
